# stack on v3: P2 rope-table loads issued together, P10 residual loads prefetched one tile ahead, P3 QK K-fragment LDS reads issued up front
# speedup vs baseline: 1.0376x; 1.0040x over previous
;     DI void operator()(int fbase, int tbase, const f32x16& acc, int r, int hh) const {
;     ...
;             if (latent) {
;                 const int pos = t & (SEQ - 1);
;                 const int pp = (fbase & 32) ? (pos & 63) : (pos >> 6);
;                 const f32x2* tab = ropeA + pp * 16;
; #pragma unroll
;                 for (int i = 0; i < 8; ++i) {
;                     const int j = (i & 3) + 8 * (i >> 2) + 4 * hh;
;                     const f32x2 cs = tab[j];
;                     const float a = acc[i], b = acc[i + 8];
;                     v[i] = a * cs.x - b * cs.y; v[i + 8] = b * cs.x + a * cs.y;
;                 }
;             }
.LBB0_210:
.LBB0_211:
	s_or_saveexec_b64 s[8:9], s[8:9]
	v_ashrrev_i32_e32 v175, 31, v132
	v_mov_b32_e32 v174, v132
	s_xor_b64 exec, exec, s[8:9]
	s_cbranch_execz .LBB0_219
	s_and_saveexec_b64 s[10:11], s[6:7]
	s_cbranch_execz .LBB0_214
	v_lshlrev_b32_e32 v128, 1, v194
	v_and_b32_e32 v128, 0x3f00, v128
	v_mov_b32_e32 v129, v133
	v_lshl_add_u64 v[178:179], v[162:163], 0, v[128:129]
	global_load_dwordx4 v[212:215], v[178:179], off
	global_load_dwordx4 v[216:219], v[178:179], off offset:16
	global_load_dwordx4 v[220:223], v[178:179], off offset:64
	global_load_dwordx4 v[224:227], v[178:179], off offset:80
	s_waitcnt vmcnt(3) lgkmcnt(0)
	v_mov_b32_e32 v128, v212
	v_mov_b32_e32 v129, v213
	v_mov_b32_e32 v130, v214
	v_mov_b32_e32 v131, v215
	v_mov_b32_e32 v197, v130
	v_mov_b32_e32 v130, v129
	v_mov_b32_e32 v196, v128
	v_pk_mul_f32 v[128:129], v[120:121], v[130:131]
	s_nop 0
	v_pk_fma_f32 v[198:199], v[112:113], v[196:197], v[128:129] neg_lo:[0,0,1] neg_hi:[0,0,1]
	v_pk_mul_f32 v[112:113], v[112:113], v[130:131]
	v_pk_fma_f32 v[120:121], v[120:121], v[196:197], v[112:113]
	s_waitcnt vmcnt(2) lgkmcnt(0)
	v_mov_b32_e32 v128, v216
	v_mov_b32_e32 v129, v217
	v_mov_b32_e32 v130, v218
	v_mov_b32_e32 v131, v219
	v_mov_b32_e32 v113, v130
	v_mov_b32_e32 v130, v129
	v_mov_b32_e32 v112, v128
	v_pk_mul_f32 v[128:129], v[122:123], v[130:131]
	s_nop 0
	v_pk_fma_f32 v[128:129], v[114:115], v[112:113], v[128:129] neg_lo:[0,0,1] neg_hi:[0,0,1]
	v_pk_mul_f32 v[114:115], v[114:115], v[130:131]
	s_nop 0
	v_pk_fma_f32 v[122:123], v[122:123], v[112:113], v[114:115]
	s_waitcnt vmcnt(1) lgkmcnt(0)
	v_mov_b32_e32 v112, v220
	v_mov_b32_e32 v113, v221
	v_mov_b32_e32 v114, v222
	v_mov_b32_e32 v115, v223
	v_mov_b32_e32 v131, v114
	v_mov_b32_e32 v114, v113
	v_mov_b32_e32 v130, v112
	v_pk_mul_f32 v[112:113], v[124:125], v[114:115]
	s_nop 0
	v_pk_fma_f32 v[196:197], v[116:117], v[130:131], v[112:113] neg_lo:[0,0,1] neg_hi:[0,0,1]
	v_pk_mul_f32 v[112:113], v[116:117], v[114:115]
	s_nop 0
	v_pk_fma_f32 v[124:125], v[124:125], v[130:131], v[112:113]
	s_waitcnt vmcnt(0) lgkmcnt(0)
	v_mov_b32_e32 v112, v224
	v_mov_b32_e32 v113, v225
	v_mov_b32_e32 v114, v226
	v_mov_b32_e32 v115, v227
	v_mul_f32_e32 v116, v126, v112
	v_mul_f32_e32 v130, v118, v113
	v_mov_b32_e32 v178, v112
	v_mov_b32_e32 v112, v113
	v_mov_b32_e32 v113, v115
	v_mov_b32_e32 v179, v114
	v_pk_mul_f32 v[112:113], v[126:127], v[112:113]
	s_nop 0
	v_pk_fma_f32 v[178:179], v[118:119], v[178:179], v[112:113] neg_lo:[0,0,1] neg_hi:[0,0,1]
	v_mov_b32_e32 v118, v127
	v_pk_mul_f32 v[112:113], v[118:119], v[114:115]
	v_mov_b32_e32 v114, v128
	v_mov_b32_e32 v117, v112
	v_mov_b32_e32 v131, v113
	v_pk_add_f32 v[126:127], v[116:117], v[130:131]
	v_mov_b32_e32 v112, v198
	v_mov_b32_e32 v113, v199
	v_mov_b32_e32 v115, v129
	v_mov_b32_e32 v116, v196
	v_mov_b32_e32 v117, v197
	v_mov_b32_e32 v118, v178
	v_mov_b32_e32 v119, v179

;     DI void operator()(int fbase, int tbase, const f32x16& acc, int r, int hh) const {
;     ...
;             if (latent) {
;                 const int pos = t & (SEQ - 1);
;                 const int pp = (fbase & 32) ? (pos & 63) : (pos >> 6);
;                 const f32x2* tab = ropeA + pp * 16;
; #pragma unroll
;                 for (int i = 0; i < 8; ++i) {
;                     const int j = (i & 3) + 8 * (i >> 2) + 4 * hh;
;                     const f32x2 cs = tab[j];
;                     const float a = acc[i], b = acc[i + 8];
;                     v[i] = a * cs.x - b * cs.y; v[i + 8] = b * cs.x + a * cs.y;
;                 }
;             }
.LBB0_224:
.LBB0_225:
	s_andn2_saveexec_b64 s[8:9], s[8:9]
	s_cbranch_execz .LBB0_233
	s_and_saveexec_b64 s[12:13], s[10:11]
	s_cbranch_execz .LBB0_228
	v_lshlrev_b32_e32 v112, 1, v194
	v_and_b32_e32 v112, 0x3f00, v112
	v_mov_b32_e32 v113, v133
	v_lshl_add_u64 v[118:119], v[162:163], 0, v[112:113]
	global_load_dwordx4 v[212:215], v[118:119], off
	global_load_dwordx4 v[216:219], v[118:119], off offset:16
	global_load_dwordx4 v[220:223], v[118:119], off offset:64
	global_load_dwordx4 v[224:227], v[118:119], off offset:80
	s_waitcnt vmcnt(3) lgkmcnt(0)
	v_mov_b32_e32 v112, v212
	v_mov_b32_e32 v113, v213
	v_mov_b32_e32 v114, v214
	v_mov_b32_e32 v115, v215
	v_mov_b32_e32 v121, v114
	v_mov_b32_e32 v114, v113
	v_mov_b32_e32 v120, v112
	v_pk_mul_f32 v[112:113], v[104:105], v[114:115]
	s_nop 0
	v_pk_fma_f32 v[122:123], v[96:97], v[120:121], v[112:113] neg_lo:[0,0,1] neg_hi:[0,0,1]
	v_pk_mul_f32 v[96:97], v[96:97], v[114:115]
	v_pk_fma_f32 v[104:105], v[104:105], v[120:121], v[96:97]
	s_waitcnt vmcnt(2) lgkmcnt(0)
	v_mov_b32_e32 v112, v216
	v_mov_b32_e32 v113, v217
	v_mov_b32_e32 v114, v218
	v_mov_b32_e32 v115, v219
	v_mov_b32_e32 v97, v114
	v_mov_b32_e32 v114, v113
	v_mov_b32_e32 v96, v112
	v_pk_mul_f32 v[112:113], v[106:107], v[114:115]
	s_nop 0
	v_pk_fma_f32 v[112:113], v[98:99], v[96:97], v[112:113] neg_lo:[0,0,1] neg_hi:[0,0,1]
	v_pk_mul_f32 v[98:99], v[98:99], v[114:115]
	s_nop 0
	v_pk_fma_f32 v[106:107], v[106:107], v[96:97], v[98:99]
	s_waitcnt vmcnt(1) lgkmcnt(0)
	v_mov_b32_e32 v96, v220
	v_mov_b32_e32 v97, v221
	v_mov_b32_e32 v98, v222
	v_mov_b32_e32 v99, v223
	v_mov_b32_e32 v115, v98
	v_mov_b32_e32 v98, v97
	v_mov_b32_e32 v114, v96
	v_pk_mul_f32 v[96:97], v[108:109], v[98:99]
	s_nop 0
	v_pk_fma_f32 v[120:121], v[100:101], v[114:115], v[96:97] neg_lo:[0,0,1] neg_hi:[0,0,1]
	v_pk_mul_f32 v[96:97], v[100:101], v[98:99]
	s_nop 0
	v_pk_fma_f32 v[108:109], v[108:109], v[114:115], v[96:97]
	s_waitcnt vmcnt(0) lgkmcnt(0)
	v_mov_b32_e32 v96, v224
	v_mov_b32_e32 v97, v225
	v_mov_b32_e32 v98, v226
	v_mov_b32_e32 v99, v227
	v_mul_f32_e32 v100, v110, v96
	v_mul_f32_e32 v114, v102, v97
	v_mov_b32_e32 v118, v96
	v_mov_b32_e32 v96, v97
	v_mov_b32_e32 v97, v99
	v_mov_b32_e32 v119, v98
	v_pk_mul_f32 v[96:97], v[110:111], v[96:97]
	s_nop 0
	v_pk_fma_f32 v[118:119], v[102:103], v[118:119], v[96:97] neg_lo:[0,0,1] neg_hi:[0,0,1]
	v_mov_b32_e32 v102, v111
	v_pk_mul_f32 v[96:97], v[102:103], v[98:99]
	v_mov_b32_e32 v98, v112
	v_mov_b32_e32 v101, v96
	v_mov_b32_e32 v115, v97
	v_pk_add_f32 v[110:111], v[100:101], v[114:115]
	v_mov_b32_e32 v96, v122
	v_mov_b32_e32 v97, v123
	v_mov_b32_e32 v99, v113
	v_mov_b32_e32 v100, v120
	v_mov_b32_e32 v101, v121
	v_mov_b32_e32 v102, v118
	v_mov_b32_e32 v103, v119

;     DI void operator()(int fbase, int tbase, const f32x16& acc, int r, int hh) const {
;     ...
;             if (latent) {
;                 const int pos = t & (SEQ - 1);
;                 const int pp = (fbase & 32) ? (pos & 63) : (pos >> 6);
;                 const f32x2* tab = ropeA + pp * 16;
; #pragma unroll
;                 for (int i = 0; i < 8; ++i) {
;                     const int j = (i & 3) + 8 * (i >> 2) + 4 * hh;
;                     const f32x2 cs = tab[j];
;                     const float a = acc[i], b = acc[i + 8];
;                     v[i] = a * cs.x - b * cs.y; v[i + 8] = b * cs.x + a * cs.y;
;                 }
;             }
.LBB0_238:
.LBB0_239:
	s_andn2_saveexec_b64 s[8:9], s[8:9]
	s_cbranch_execz .LBB0_247
	s_and_saveexec_b64 s[18:19], s[12:13]
	s_cbranch_execz .LBB0_242
	v_lshlrev_b32_e32 v96, 1, v101
	v_and_b32_e32 v96, 0x3f80, v96
	v_mov_b32_e32 v97, v133
	v_lshl_add_u64 v[102:103], v[162:163], 0, v[96:97]
	global_load_dwordx4 v[212:215], v[102:103], off
	global_load_dwordx4 v[216:219], v[102:103], off offset:16
	global_load_dwordx4 v[220:223], v[102:103], off offset:64
	global_load_dwordx4 v[224:227], v[102:103], off offset:80
	s_waitcnt vmcnt(3) lgkmcnt(0)
	v_mov_b32_e32 v96, v212
	v_mov_b32_e32 v97, v213
	v_mov_b32_e32 v98, v214
	v_mov_b32_e32 v99, v215
	v_mov_b32_e32 v105, v98
	v_mov_b32_e32 v98, v97
	v_mov_b32_e32 v104, v96
	v_pk_mul_f32 v[96:97], v[88:89], v[98:99]
	s_nop 0
	v_pk_fma_f32 v[106:107], v[80:81], v[104:105], v[96:97] neg_lo:[0,0,1] neg_hi:[0,0,1]
	v_pk_mul_f32 v[80:81], v[80:81], v[98:99]
	v_pk_fma_f32 v[88:89], v[88:89], v[104:105], v[80:81]
	s_waitcnt vmcnt(2) lgkmcnt(0)
	v_mov_b32_e32 v96, v216
	v_mov_b32_e32 v97, v217
	v_mov_b32_e32 v98, v218
	v_mov_b32_e32 v99, v219
	v_mov_b32_e32 v81, v98
	v_mov_b32_e32 v98, v97
	v_mov_b32_e32 v80, v96
	v_pk_mul_f32 v[96:97], v[90:91], v[98:99]
	s_nop 0
	v_pk_fma_f32 v[96:97], v[82:83], v[80:81], v[96:97] neg_lo:[0,0,1] neg_hi:[0,0,1]
	v_pk_mul_f32 v[82:83], v[82:83], v[98:99]
	s_nop 0
	v_pk_fma_f32 v[90:91], v[90:91], v[80:81], v[82:83]
	s_waitcnt vmcnt(1) lgkmcnt(0)
	v_mov_b32_e32 v80, v220
	v_mov_b32_e32 v81, v221
	v_mov_b32_e32 v82, v222
	v_mov_b32_e32 v83, v223
	v_mov_b32_e32 v99, v82
	v_mov_b32_e32 v82, v81
	v_mov_b32_e32 v98, v80
	v_pk_mul_f32 v[80:81], v[92:93], v[82:83]
	s_nop 0
	v_pk_fma_f32 v[104:105], v[84:85], v[98:99], v[80:81] neg_lo:[0,0,1] neg_hi:[0,0,1]
	v_pk_mul_f32 v[80:81], v[84:85], v[82:83]
	s_nop 0
	v_pk_fma_f32 v[92:93], v[92:93], v[98:99], v[80:81]
	s_waitcnt vmcnt(0) lgkmcnt(0)
	v_mov_b32_e32 v80, v224
	v_mov_b32_e32 v81, v225
	v_mov_b32_e32 v82, v226
	v_mov_b32_e32 v83, v227
	v_mul_f32_e32 v84, v94, v80
	v_mul_f32_e32 v98, v86, v81
	v_mov_b32_e32 v102, v80
	v_mov_b32_e32 v80, v81
	v_mov_b32_e32 v81, v83
	v_mov_b32_e32 v103, v82
	v_pk_mul_f32 v[80:81], v[94:95], v[80:81]
	s_nop 0
	v_pk_fma_f32 v[102:103], v[86:87], v[102:103], v[80:81] neg_lo:[0,0,1] neg_hi:[0,0,1]
	v_mov_b32_e32 v86, v95
	v_pk_mul_f32 v[80:81], v[86:87], v[82:83]
	v_mov_b32_e32 v82, v96
	v_mov_b32_e32 v85, v80
	v_mov_b32_e32 v99, v81
	v_pk_add_f32 v[94:95], v[84:85], v[98:99]
	v_mov_b32_e32 v80, v106
	v_mov_b32_e32 v81, v107
	v_mov_b32_e32 v83, v97
	v_mov_b32_e32 v84, v104
	v_mov_b32_e32 v85, v105
	v_mov_b32_e32 v86, v102
	v_mov_b32_e32 v87, v103

;     DI void operator()(int fbase, int tbase, const f32x16& acc, int r, int hh) const {
;     ...
;             if (latent) {
;                 const int pos = t & (SEQ - 1);
;                 const int pp = (fbase & 32) ? (pos & 63) : (pos >> 6);
;                 const f32x2* tab = ropeA + pp * 16;
; #pragma unroll
;                 for (int i = 0; i < 8; ++i) {
;                     const int j = (i & 3) + 8 * (i >> 2) + 4 * hh;
;                     const f32x2 cs = tab[j];
;                     const float a = acc[i], b = acc[i + 8];
;                     v[i] = a * cs.x - b * cs.y; v[i + 8] = b * cs.x + a * cs.y;
;                 }
;             }
.LBB0_252:
.LBB0_253:
	s_andn2_saveexec_b64 s[16:17], s[16:17]
	s_cbranch_execz .LBB0_261
	s_and_saveexec_b64 s[18:19], s[8:9]
	s_cbranch_execz .LBB0_256
	v_lshlrev_b32_e32 v80, 1, v85
	v_and_b32_e32 v80, 0x3f80, v80
	v_mov_b32_e32 v81, v133
	v_lshl_add_u64 v[86:87], v[162:163], 0, v[80:81]
	global_load_dwordx4 v[212:215], v[86:87], off
	global_load_dwordx4 v[216:219], v[86:87], off offset:16
	global_load_dwordx4 v[220:223], v[86:87], off offset:64
	global_load_dwordx4 v[224:227], v[86:87], off offset:80
	s_waitcnt vmcnt(3) lgkmcnt(0)
	v_mov_b32_e32 v80, v212
	v_mov_b32_e32 v81, v213
	v_mov_b32_e32 v82, v214
	v_mov_b32_e32 v83, v215
	v_mov_b32_e32 v89, v82
	v_mov_b32_e32 v82, v81
	v_mov_b32_e32 v88, v80
	v_pk_mul_f32 v[80:81], v[72:73], v[82:83]
	s_nop 0
	v_pk_fma_f32 v[90:91], v[64:65], v[88:89], v[80:81] neg_lo:[0,0,1] neg_hi:[0,0,1]
	v_pk_mul_f32 v[64:65], v[64:65], v[82:83]
	v_pk_fma_f32 v[72:73], v[72:73], v[88:89], v[64:65]
	s_waitcnt vmcnt(2) lgkmcnt(0)
	v_mov_b32_e32 v80, v216
	v_mov_b32_e32 v81, v217
	v_mov_b32_e32 v82, v218
	v_mov_b32_e32 v83, v219
	v_mov_b32_e32 v65, v82
	v_mov_b32_e32 v82, v81
	v_mov_b32_e32 v64, v80
	v_pk_mul_f32 v[80:81], v[74:75], v[82:83]
	s_nop 0
	v_pk_fma_f32 v[80:81], v[66:67], v[64:65], v[80:81] neg_lo:[0,0,1] neg_hi:[0,0,1]
	v_pk_mul_f32 v[66:67], v[66:67], v[82:83]
	s_nop 0
	v_pk_fma_f32 v[74:75], v[74:75], v[64:65], v[66:67]
	s_waitcnt vmcnt(1) lgkmcnt(0)
	v_mov_b32_e32 v64, v220
	v_mov_b32_e32 v65, v221
	v_mov_b32_e32 v66, v222
	v_mov_b32_e32 v67, v223
	v_mov_b32_e32 v83, v66
	v_mov_b32_e32 v66, v65
	v_mov_b32_e32 v82, v64
	v_pk_mul_f32 v[64:65], v[76:77], v[66:67]
	s_nop 0
	v_pk_fma_f32 v[88:89], v[68:69], v[82:83], v[64:65] neg_lo:[0,0,1] neg_hi:[0,0,1]
	v_pk_mul_f32 v[64:65], v[68:69], v[66:67]
	s_nop 0
	v_pk_fma_f32 v[76:77], v[76:77], v[82:83], v[64:65]
	s_waitcnt vmcnt(0) lgkmcnt(0)
	v_mov_b32_e32 v64, v224
	v_mov_b32_e32 v65, v225
	v_mov_b32_e32 v66, v226
	v_mov_b32_e32 v67, v227
	v_mul_f32_e32 v68, v78, v64
	v_mul_f32_e32 v82, v70, v65
	v_mov_b32_e32 v86, v64
	v_mov_b32_e32 v64, v65
	v_mov_b32_e32 v65, v67
	v_mov_b32_e32 v87, v66
	v_pk_mul_f32 v[64:65], v[78:79], v[64:65]
	s_nop 0
	v_pk_fma_f32 v[86:87], v[70:71], v[86:87], v[64:65] neg_lo:[0,0,1] neg_hi:[0,0,1]
	v_mov_b32_e32 v70, v79
	v_pk_mul_f32 v[64:65], v[70:71], v[66:67]
	v_mov_b32_e32 v66, v80
	v_mov_b32_e32 v69, v64
	v_mov_b32_e32 v83, v65
	v_pk_add_f32 v[78:79], v[68:69], v[82:83]
	v_mov_b32_e32 v64, v90
	v_mov_b32_e32 v65, v91
	v_mov_b32_e32 v67, v81
	v_mov_b32_e32 v68, v88
	v_mov_b32_e32 v69, v89
	v_mov_b32_e32 v70, v86
	v_mov_b32_e32 v71, v87

;     DI void operator()(int fbase, int tbase, const f32x16& acc, int r, int hh) const {
;     ...
;             if (latent) {
;                 const int pos = t & (SEQ - 1);
;                 const int pp = (fbase & 32) ? (pos & 63) : (pos >> 6);
;                 const f32x2* tab = ropeA + pp * 16;
; #pragma unroll
;                 for (int i = 0; i < 8; ++i) {
;                     const int j = (i & 3) + 8 * (i >> 2) + 4 * hh;
;                     const f32x2 cs = tab[j];
;                     const float a = acc[i], b = acc[i + 8];
;                     v[i] = a * cs.x - b * cs.y; v[i + 8] = b * cs.x + a * cs.y;
;                 }
;             }
.LBB0_266:
.LBB0_267:
	s_andn2_saveexec_b64 vcc, s[18:19]
	s_cbranch_execz .LBB0_275
	s_and_saveexec_b64 s[18:19], s[6:7]
	s_cbranch_execz .LBB0_270
	global_load_dwordx4 v[212:215], v[164:165], off
	global_load_dwordx4 v[216:219], v[164:165], off offset:16
	global_load_dwordx4 v[220:223], v[164:165], off offset:64
	global_load_dwordx4 v[224:227], v[164:165], off offset:80
	s_waitcnt vmcnt(3) lgkmcnt(0)
	v_mov_b32_e32 v64, v212
	v_mov_b32_e32 v65, v213
	v_mov_b32_e32 v66, v214
	v_mov_b32_e32 v67, v215
	v_mov_b32_e32 v69, v66
	v_mov_b32_e32 v66, v65
	v_mov_b32_e32 v68, v64
	v_pk_mul_f32 v[64:65], v[56:57], v[66:67]
	s_nop 0
	v_pk_fma_f32 v[72:73], v[48:49], v[68:69], v[64:65] neg_lo:[0,0,1] neg_hi:[0,0,1]
	v_pk_mul_f32 v[48:49], v[48:49], v[66:67]
	v_pk_fma_f32 v[56:57], v[56:57], v[68:69], v[48:49]
	s_waitcnt vmcnt(2) lgkmcnt(0)
	v_mov_b32_e32 v64, v216
	v_mov_b32_e32 v65, v217
	v_mov_b32_e32 v66, v218
	v_mov_b32_e32 v67, v219
	v_mov_b32_e32 v49, v66
	v_mov_b32_e32 v66, v65
	v_mov_b32_e32 v48, v64
	v_pk_mul_f32 v[64:65], v[58:59], v[66:67]
	s_nop 0
	v_pk_fma_f32 v[64:65], v[50:51], v[48:49], v[64:65] neg_lo:[0,0,1] neg_hi:[0,0,1]
	v_pk_mul_f32 v[50:51], v[50:51], v[66:67]
	s_nop 0
	v_pk_fma_f32 v[58:59], v[58:59], v[48:49], v[50:51]
	s_waitcnt vmcnt(1) lgkmcnt(0)
	v_mov_b32_e32 v48, v220
	v_mov_b32_e32 v49, v221
	v_mov_b32_e32 v50, v222
	v_mov_b32_e32 v51, v223
	v_mov_b32_e32 v67, v50
	v_mov_b32_e32 v50, v49
	v_mov_b32_e32 v66, v48
	v_pk_mul_f32 v[48:49], v[60:61], v[50:51]
	s_nop 0
	v_pk_fma_f32 v[68:69], v[52:53], v[66:67], v[48:49] neg_lo:[0,0,1] neg_hi:[0,0,1]
	v_pk_mul_f32 v[48:49], v[52:53], v[50:51]
	s_nop 0
	v_pk_fma_f32 v[60:61], v[60:61], v[66:67], v[48:49]
	s_waitcnt vmcnt(0) lgkmcnt(0)
	v_mov_b32_e32 v48, v224
	v_mov_b32_e32 v49, v225
	v_mov_b32_e32 v50, v226
	v_mov_b32_e32 v51, v227
	v_mul_f32_e32 v52, v62, v48
	v_mul_f32_e32 v66, v54, v49
	v_mov_b32_e32 v74, v48
	v_mov_b32_e32 v48, v49
	v_mov_b32_e32 v49, v51
	v_mov_b32_e32 v75, v50
	v_pk_mul_f32 v[48:49], v[62:63], v[48:49]
	s_nop 0
	v_pk_fma_f32 v[74:75], v[54:55], v[74:75], v[48:49] neg_lo:[0,0,1] neg_hi:[0,0,1]
	v_mov_b32_e32 v54, v63
	v_pk_mul_f32 v[48:49], v[54:55], v[50:51]
	v_mov_b32_e32 v50, v64
	v_mov_b32_e32 v53, v48
	v_mov_b32_e32 v67, v49
	v_pk_add_f32 v[62:63], v[52:53], v[66:67]
	v_mov_b32_e32 v48, v72
	v_mov_b32_e32 v49, v73
	v_mov_b32_e32 v51, v65
	v_mov_b32_e32 v52, v68
	v_mov_b32_e32 v53, v69
	v_mov_b32_e32 v54, v74
	v_mov_b32_e32 v55, v75

;     DI void operator()(int fbase, int tbase, const f32x16& acc, int r, int hh) const {
;     ...
;             if (latent) {
;                 const int pos = t & (SEQ - 1);
;                 const int pp = (fbase & 32) ? (pos & 63) : (pos >> 6);
;                 const f32x2* tab = ropeA + pp * 16;
; #pragma unroll
;                 for (int i = 0; i < 8; ++i) {
;                     const int j = (i & 3) + 8 * (i >> 2) + 4 * hh;
;                     const f32x2 cs = tab[j];
;                     const float a = acc[i], b = acc[i + 8];
;                     v[i] = a * cs.x - b * cs.y; v[i + 8] = b * cs.x + a * cs.y;
;                 }
;             }
.LBB0_280:
.LBB0_281:
	s_andn2_saveexec_b64 s[6:7], s[6:7]
	s_cbranch_execz .LBB0_289
	s_and_saveexec_b64 s[18:19], s[10:11]
	s_cbranch_execz .LBB0_284
	global_load_dwordx4 v[212:215], v[166:167], off
	global_load_dwordx4 v[216:219], v[166:167], off offset:16
	global_load_dwordx4 v[220:223], v[166:167], off offset:64
	global_load_dwordx4 v[224:227], v[166:167], off offset:80
	s_waitcnt vmcnt(3) lgkmcnt(0)
	v_mov_b32_e32 v48, v212
	v_mov_b32_e32 v49, v213
	v_mov_b32_e32 v50, v214
	v_mov_b32_e32 v51, v215
	v_mov_b32_e32 v53, v50
	v_mov_b32_e32 v50, v49
	v_mov_b32_e32 v52, v48
	v_pk_mul_f32 v[48:49], v[40:41], v[50:51]
	s_nop 0
	v_pk_fma_f32 v[54:55], v[32:33], v[52:53], v[48:49] neg_lo:[0,0,1] neg_hi:[0,0,1]
	v_pk_mul_f32 v[32:33], v[32:33], v[50:51]
	v_pk_fma_f32 v[40:41], v[40:41], v[52:53], v[32:33]
	s_waitcnt vmcnt(2) lgkmcnt(0)
	v_mov_b32_e32 v48, v216
	v_mov_b32_e32 v49, v217
	v_mov_b32_e32 v50, v218
	v_mov_b32_e32 v51, v219
	v_mov_b32_e32 v33, v50
	v_mov_b32_e32 v50, v49
	v_mov_b32_e32 v32, v48
	v_pk_mul_f32 v[48:49], v[42:43], v[50:51]
	s_nop 0
	v_pk_fma_f32 v[48:49], v[34:35], v[32:33], v[48:49] neg_lo:[0,0,1] neg_hi:[0,0,1]
	v_pk_mul_f32 v[34:35], v[34:35], v[50:51]
	s_nop 0
	v_pk_fma_f32 v[42:43], v[42:43], v[32:33], v[34:35]
	s_waitcnt vmcnt(1) lgkmcnt(0)
	v_mov_b32_e32 v32, v220
	v_mov_b32_e32 v33, v221
	v_mov_b32_e32 v34, v222
	v_mov_b32_e32 v35, v223
	v_mov_b32_e32 v51, v34
	v_mov_b32_e32 v34, v33
	v_mov_b32_e32 v50, v32
	v_pk_mul_f32 v[32:33], v[44:45], v[34:35]
	s_nop 0
	v_pk_fma_f32 v[52:53], v[36:37], v[50:51], v[32:33] neg_lo:[0,0,1] neg_hi:[0,0,1]
	v_pk_mul_f32 v[32:33], v[36:37], v[34:35]
	s_nop 0
	v_pk_fma_f32 v[44:45], v[44:45], v[50:51], v[32:33]
	s_waitcnt vmcnt(0) lgkmcnt(0)
	v_mov_b32_e32 v32, v224
	v_mov_b32_e32 v33, v225
	v_mov_b32_e32 v34, v226
	v_mov_b32_e32 v35, v227
	v_mul_f32_e32 v36, v46, v32
	v_mul_f32_e32 v50, v38, v33
	v_mov_b32_e32 v56, v32
	v_mov_b32_e32 v32, v33
	v_mov_b32_e32 v33, v35
	v_mov_b32_e32 v57, v34
	v_pk_mul_f32 v[32:33], v[46:47], v[32:33]
	s_nop 0
	v_pk_fma_f32 v[56:57], v[38:39], v[56:57], v[32:33] neg_lo:[0,0,1] neg_hi:[0,0,1]
	v_mov_b32_e32 v38, v47
	v_pk_mul_f32 v[32:33], v[38:39], v[34:35]
	v_mov_b32_e32 v34, v48
	v_mov_b32_e32 v37, v32
	v_mov_b32_e32 v51, v33
	v_pk_add_f32 v[46:47], v[36:37], v[50:51]
	v_mov_b32_e32 v32, v54
	v_mov_b32_e32 v33, v55
	v_mov_b32_e32 v35, v49
	v_mov_b32_e32 v36, v52
	v_mov_b32_e32 v37, v53
	v_mov_b32_e32 v38, v56
	v_mov_b32_e32 v39, v57

;     DI void operator()(int fbase, int tbase, const f32x16& acc, int r, int hh) const {
;     ...
;             if (latent) {
;                 const int pos = t & (SEQ - 1);
;                 const int pp = (fbase & 32) ? (pos & 63) : (pos >> 6);
;                 const f32x2* tab = ropeA + pp * 16;
; #pragma unroll
;                 for (int i = 0; i < 8; ++i) {
;                     const int j = (i & 3) + 8 * (i >> 2) + 4 * hh;
;                     const f32x2 cs = tab[j];
;                     const float a = acc[i], b = acc[i + 8];
;                     v[i] = a * cs.x - b * cs.y; v[i + 8] = b * cs.x + a * cs.y;
;                 }
;             }
.LBB0_294:
.LBB0_295:
	s_andn2_saveexec_b64 s[6:7], s[6:7]
	s_cbranch_execz .LBB0_303
	s_and_saveexec_b64 s[10:11], s[12:13]
	s_cbranch_execz .LBB0_298
	global_load_dwordx4 v[212:215], v[164:165], off
	global_load_dwordx4 v[216:219], v[164:165], off offset:16
	global_load_dwordx4 v[220:223], v[164:165], off offset:64
	global_load_dwordx4 v[224:227], v[164:165], off offset:80
	s_waitcnt vmcnt(3) lgkmcnt(0)
	v_mov_b32_e32 v32, v212
	v_mov_b32_e32 v33, v213
	v_mov_b32_e32 v34, v214
	v_mov_b32_e32 v35, v215
	v_mov_b32_e32 v37, v34
	v_mov_b32_e32 v34, v33
	v_mov_b32_e32 v36, v32
	v_pk_mul_f32 v[32:33], v[24:25], v[34:35]
	s_nop 0
	v_pk_fma_f32 v[38:39], v[16:17], v[36:37], v[32:33] neg_lo:[0,0,1] neg_hi:[0,0,1]
	v_pk_mul_f32 v[16:17], v[16:17], v[34:35]
	v_pk_fma_f32 v[24:25], v[24:25], v[36:37], v[16:17]
	s_waitcnt vmcnt(2) lgkmcnt(0)
	v_mov_b32_e32 v32, v216
	v_mov_b32_e32 v33, v217
	v_mov_b32_e32 v34, v218
	v_mov_b32_e32 v35, v219
	v_mov_b32_e32 v17, v34
	v_mov_b32_e32 v34, v33
	v_mov_b32_e32 v16, v32
	v_pk_mul_f32 v[32:33], v[26:27], v[34:35]
	s_nop 0
	v_pk_fma_f32 v[32:33], v[18:19], v[16:17], v[32:33] neg_lo:[0,0,1] neg_hi:[0,0,1]
	v_pk_mul_f32 v[18:19], v[18:19], v[34:35]
	s_nop 0
	v_pk_fma_f32 v[26:27], v[26:27], v[16:17], v[18:19]
	s_waitcnt vmcnt(1) lgkmcnt(0)
	v_mov_b32_e32 v16, v220
	v_mov_b32_e32 v17, v221
	v_mov_b32_e32 v18, v222
	v_mov_b32_e32 v19, v223
	v_mov_b32_e32 v35, v18
	v_mov_b32_e32 v18, v17
	v_mov_b32_e32 v34, v16
	v_pk_mul_f32 v[16:17], v[28:29], v[18:19]
	s_nop 0
	v_pk_fma_f32 v[36:37], v[20:21], v[34:35], v[16:17] neg_lo:[0,0,1] neg_hi:[0,0,1]
	v_pk_mul_f32 v[16:17], v[20:21], v[18:19]
	s_nop 0
	v_pk_fma_f32 v[28:29], v[28:29], v[34:35], v[16:17]
	s_waitcnt vmcnt(0) lgkmcnt(0)
	v_mov_b32_e32 v16, v224
	v_mov_b32_e32 v17, v225
	v_mov_b32_e32 v18, v226
	v_mov_b32_e32 v19, v227
	v_mul_f32_e32 v20, v30, v16
	v_mul_f32_e32 v34, v22, v17
	v_mov_b32_e32 v40, v16
	v_mov_b32_e32 v16, v17
	v_mov_b32_e32 v17, v19
	v_mov_b32_e32 v41, v18
	v_pk_mul_f32 v[16:17], v[30:31], v[16:17]
	s_nop 0
	v_pk_fma_f32 v[40:41], v[22:23], v[40:41], v[16:17] neg_lo:[0,0,1] neg_hi:[0,0,1]
	v_mov_b32_e32 v22, v31
	v_pk_mul_f32 v[16:17], v[22:23], v[18:19]
	v_mov_b32_e32 v18, v32
	v_mov_b32_e32 v21, v16
	v_mov_b32_e32 v35, v17
	v_pk_add_f32 v[30:31], v[20:21], v[34:35]
	v_mov_b32_e32 v16, v38
	v_mov_b32_e32 v17, v39
	v_mov_b32_e32 v19, v33
	v_mov_b32_e32 v20, v36
	v_mov_b32_e32 v21, v37
	v_mov_b32_e32 v22, v40
	v_mov_b32_e32 v23, v41

; #define MFMA(a, b, c) __builtin_amdgcn_mfma_f32_32x32x16_bf16((a), (b), (c), 0, 0, 0)
; DI void attn_a_phase(const Params& p, unsigned char* ws, unsigned char* lds, int tid) {
;     ...
;                 f32x16 S[2][2];
; #pragma unroll
;                 for (int e = 0; e < 2; ++e)
; #pragma unroll
;                     for (int sb = 0; sb < 2; ++sb)
; #pragma unroll
;                         for (int i = 0; i < 16; ++i) S[e][sb][i] = 0.f;
; #pragma unroll
;                 for (int sb = 0; sb < 2; ++sb)
; #pragma unroll
;                     for (int ks = 0; ks < 4; ++ks) {
;                         const bf16x8 kf = *(const bf16x8*)(kl + (sb * 32 + pr) * 144 + ks * 32 + hh * 16);
;                         S[0][sb] = MFMA(kf, qf[0][ks], S[0][sb]);
;                         S[1][sb] = MFMA(kf, qf[1][ks], S[1][sb]);
;                     }
;                 if (masked && !(kpos0 >= qlo - 97 && kpos0 <= qlo + 65)) {
;                     const int qp = qlo + r;
; #pragma unroll
;                     for (int sb = 0; sb < 2; ++sb)
; #pragma unroll
;                         for (int i = 0; i < 16; ++i) {
;                             const int kp = kpos0 + sb * 32 + 16 * (i >> 3) + 8 * hh + (i & 7);
;                             const int dlt = qp - kp;
;                             if (dlt > 128 || dlt < -128) { S[0][sb][i] = -1e30f; S[1][sb][i] = -1e30f; }
;                         }
.LBB0_412:
	s_bitcmp1_b32 s58, 0
	s_cselect_b32 s4, 0x4800, 0
	v_add_u32_e32 v0, s4, v211
	v_add_u32_e32 v10, v0, v209
	ds_read_b128 v[2:5], v10
	ds_read_b128 v[6:9], v10 offset:32
	ds_read_b128 v[224:227], v10 offset:64
	ds_read_b128 v[228:231], v10 offset:96
	ds_read_b128 v[232:235], v10 offset:4608
	ds_read_b128 v[236:239], v10 offset:4640
	ds_read_b128 v[240:243], v10 offset:4672
	ds_read_b128 v[12:15], v10 offset:4704
	s_andn2_b64 vcc, exec, s[18:19]
	s_waitcnt lgkmcnt(7)
	v_mfma_f32_32x32x16_bf16 v[128:143], v[2:5], v[144:147], 0
	v_mfma_f32_32x32x16_bf16 v[96:111], v[2:5], v[160:163], 0
	s_waitcnt lgkmcnt(6)
	v_mfma_f32_32x32x16_bf16 v[128:143], v[6:9], v[148:151], v[128:143]
	v_mfma_f32_32x32x16_bf16 v[96:111], v[6:9], v[164:167], v[96:111]
	s_waitcnt lgkmcnt(5)
	v_mfma_f32_32x32x16_bf16 v[128:143], v[224:227], v[152:155], v[128:143]
	v_mfma_f32_32x32x16_bf16 v[96:111], v[224:227], v[168:171], v[96:111]
	s_waitcnt lgkmcnt(4)
	v_mfma_f32_32x32x16_bf16 v[128:143], v[228:231], v[156:159], v[128:143]
	v_mfma_f32_32x32x16_bf16 v[96:111], v[228:231], v[172:175], v[96:111]
	s_waitcnt lgkmcnt(3)
	v_mfma_f32_32x32x16_bf16 v[112:127], v[232:235], v[144:147], 0
	v_mfma_f32_32x32x16_bf16 v[80:95], v[232:235], v[160:163], 0
	s_waitcnt lgkmcnt(2)
	v_mfma_f32_32x32x16_bf16 v[112:127], v[236:239], v[148:151], v[112:127]
	v_mfma_f32_32x32x16_bf16 v[80:95], v[236:239], v[164:167], v[80:95]
	s_waitcnt lgkmcnt(1)
	v_mfma_f32_32x32x16_bf16 v[112:127], v[240:243], v[152:155], v[112:127]
	v_mfma_f32_32x32x16_bf16 v[80:95], v[240:243], v[168:171], v[80:95]
	s_waitcnt lgkmcnt(0)
	v_mfma_f32_32x32x16_bf16 v[112:127], v[12:15], v[156:159], v[112:127]
	v_mfma_f32_32x32x16_bf16 v[80:95], v[12:15], v[172:175], v[80:95]
	s_cbranch_vccnz .LBB0_416
	v_cmp_lt_i32_e32 vcc, s59, v220
	v_cmp_gt_i32_e64 s[4:5], s59, v221
	s_or_b64 s[18:19], vcc, s[4:5]
	s_and_saveexec_b64 s[4:5], s[18:19]
	s_cbranch_execz .LBB0_415
	v_add_u32_e32 v2, 55, v222
	v_cmp_gt_u32_e32 vcc, s23, v2
	v_add_u32_e32 v2, 53, v222
	s_nop 0
	v_cndmask_b32_e32 v96, v96, v214, vcc
	v_cndmask_b32_e32 v128, v128, v214, vcc
	v_cmp_lt_u32_e32 vcc, s3, v223
	s_nop 1
	v_cndmask_b32_e32 v97, v97, v214, vcc
	v_cndmask_b32_e32 v129, v129, v214, vcc
	v_cmp_gt_u32_e32 vcc, s23, v2
	v_add_u32_e32 v2, 52, v222
	s_nop 0
	v_cndmask_b32_e32 v98, v98, v214, vcc
	v_cndmask_b32_e32 v130, v130, v214, vcc
	v_cmp_gt_u32_e32 vcc, s23, v2
	v_add_u32_e32 v2, 51, v222
	s_nop 0
	v_cndmask_b32_e32 v99, v99, v214, vcc
	v_cndmask_b32_e32 v131, v131, v214, vcc
	v_cmp_gt_u32_e32 vcc, s23, v2
	v_add_u32_e32 v2, 50, v222
	s_nop 0
	v_cndmask_b32_e32 v100, v100, v214, vcc
	v_cndmask_b32_e32 v132, v132, v214, vcc
	v_cmp_gt_u32_e32 vcc, s23, v2
	v_add_u32_e32 v2, 49, v222
	s_nop 0
	v_cndmask_b32_e32 v101, v101, v214, vcc
	v_cndmask_b32_e32 v133, v133, v214, vcc
	v_cmp_gt_u32_e32 vcc, s23, v2
	v_add_u32_e32 v2, 48, v222
	s_nop 0
	v_cndmask_b32_e32 v102, v102, v214, vcc
	v_cndmask_b32_e32 v134, v134, v214, vcc
	v_cmp_gt_u32_e32 vcc, s23, v2
	v_add_u32_e32 v2, 39, v222
	s_nop 0
	v_cndmask_b32_e32 v103, v103, v214, vcc
	v_cndmask_b32_e32 v135, v135, v214, vcc
	v_cmp_gt_u32_e32 vcc, s23, v2
	v_add_u32_e32 v2, 38, v222
	s_nop 0
	v_cndmask_b32_e32 v104, v104, v214, vcc
	v_cndmask_b32_e32 v136, v136, v214, vcc
	v_cmp_gt_u32_e32 vcc, s23, v2
	v_add_u32_e32 v2, 37, v222
	s_nop 0
	v_cndmask_b32_e32 v105, v105, v214, vcc
	v_cndmask_b32_e32 v137, v137, v214, vcc
	v_cmp_gt_u32_e32 vcc, s23, v2
	v_add_u32_e32 v2, 36, v222
	s_nop 0
	v_cndmask_b32_e32 v106, v106, v214, vcc
	v_cndmask_b32_e32 v138, v138, v214, vcc
	v_cmp_gt_u32_e32 vcc, s23, v2
	v_add_u32_e32 v2, 35, v222
	s_nop 0
	v_cndmask_b32_e32 v107, v107, v214, vcc
	v_cndmask_b32_e32 v139, v139, v214, vcc
	v_cmp_gt_u32_e32 vcc, s23, v2
	v_add_u32_e32 v2, 34, v222
	s_nop 0
	v_cndmask_b32_e32 v108, v108, v214, vcc
	v_cndmask_b32_e32 v140, v140, v214, vcc
	v_cmp_gt_u32_e32 vcc, s23, v2
	v_add_u32_e32 v2, 33, v222
	s_nop 0
	v_cndmask_b32_e32 v109, v109, v214, vcc
	v_cndmask_b32_e32 v141, v141, v214, vcc
	v_cmp_gt_u32_e32 vcc, s23, v2
	v_add_u32_e32 v2, 32, v222
	s_nop 0
	v_cndmask_b32_e32 v110, v110, v214, vcc
	v_cndmask_b32_e32 v142, v142, v214, vcc
	v_cmp_gt_u32_e32 vcc, s23, v2
	v_add_u32_e32 v2, 23, v222
	s_nop 0
	v_cndmask_b32_e32 v111, v111, v214, vcc
	v_cndmask_b32_e32 v143, v143, v214, vcc
	v_cmp_gt_u32_e32 vcc, s23, v2
	v_add_u32_e32 v2, 22, v222
	s_nop 0
	v_cndmask_b32_e32 v80, v80, v214, vcc
	v_cndmask_b32_e32 v112, v112, v214, vcc
	v_cmp_gt_u32_e32 vcc, s23, v2
	v_add_u32_e32 v2, 21, v222
	s_nop 0
	v_cndmask_b32_e32 v81, v81, v214, vcc
	v_cndmask_b32_e32 v113, v113, v214, vcc
	v_cmp_gt_u32_e32 vcc, s23, v2
	v_add_u32_e32 v2, 20, v222
	s_nop 0
	v_cndmask_b32_e32 v82, v82, v214, vcc
	v_cndmask_b32_e32 v114, v114, v214, vcc
	v_cmp_gt_u32_e32 vcc, s23, v2
	v_add_u32_e32 v2, 19, v222
	s_nop 0
	v_cndmask_b32_e32 v83, v83, v214, vcc
	v_cndmask_b32_e32 v115, v115, v214, vcc
	v_cmp_gt_u32_e32 vcc, s23, v2
	v_add_u32_e32 v2, 18, v222
	s_nop 0
	v_cndmask_b32_e32 v84, v84, v214, vcc
	v_cndmask_b32_e32 v116, v116, v214, vcc
	v_cmp_gt_u32_e32 vcc, s23, v2
	v_add_u32_e32 v2, 17, v222
	s_nop 0
	v_cndmask_b32_e32 v85, v85, v214, vcc
	v_cndmask_b32_e32 v117, v117, v214, vcc
	v_cmp_gt_u32_e32 vcc, s23, v2
	v_add_u32_e32 v2, 16, v222
	s_nop 0
	v_cndmask_b32_e32 v86, v86, v214, vcc
	v_cndmask_b32_e32 v118, v118, v214, vcc
	v_cmp_gt_u32_e32 vcc, s23, v2
	v_add_u32_e32 v2, 7, v222
	s_nop 0
	v_cndmask_b32_e32 v87, v87, v214, vcc
	v_cndmask_b32_e32 v119, v119, v214, vcc
	v_cmp_gt_u32_e32 vcc, s23, v2
	v_add_u32_e32 v2, 6, v222
	s_nop 0
	v_cndmask_b32_e32 v88, v88, v214, vcc
	v_cndmask_b32_e32 v120, v120, v214, vcc
	v_cmp_gt_u32_e32 vcc, s23, v2
	v_add_u32_e32 v2, 5, v222
	s_nop 0
	v_cndmask_b32_e32 v89, v89, v214, vcc
	v_cndmask_b32_e32 v121, v121, v214, vcc
	v_cmp_gt_u32_e32 vcc, s23, v2
	v_add_u32_e32 v2, 4, v222
	s_nop 0
	v_cndmask_b32_e32 v90, v90, v214, vcc
	v_cndmask_b32_e32 v122, v122, v214, vcc
	v_cmp_gt_u32_e32 vcc, s23, v2
	v_add_u32_e32 v2, 3, v222
	s_nop 0
	v_cndmask_b32_e32 v91, v91, v214, vcc
	v_cndmask_b32_e32 v123, v123, v214, vcc
	v_cmp_gt_u32_e32 vcc, s23, v2
	v_add_u32_e32 v2, 2, v222
	s_nop 0
	v_cndmask_b32_e32 v92, v92, v214, vcc
	v_cndmask_b32_e32 v124, v124, v214, vcc
	v_cmp_gt_u32_e32 vcc, s23, v2
	v_add_u32_e32 v2, 1, v222
	s_nop 0
	v_cndmask_b32_e32 v93, v93, v214, vcc
	v_cndmask_b32_e32 v125, v125, v214, vcc
	v_cmp_gt_u32_e32 vcc, s23, v2
	s_nop 1
	v_cndmask_b32_e32 v94, v94, v214, vcc
	v_cndmask_b32_e32 v126, v126, v214, vcc
	v_cmp_gt_u32_e32 vcc, s23, v222
	s_nop 1
	v_cndmask_b32_e32 v95, v95, v214, vcc
	v_cndmask_b32_e32 v127, v127, v214, vcc

; #define GAS __attribute__((address_space(1)))
; DI float bflo(unsigned u) { return __uint_as_float(u << 16); }
; DI float bfhi(unsigned u) { return __uint_as_float(u & 0xffff0000u); }
;     ...
; #pragma unroll
;         for (int fb = 0; fb < 2; ++fb)
; #pragma unroll
;             for (int tb = 0; tb < TB; ++tb) epi(nt * 256 + wf * 64 + fb * 32, mt * RM + wt * 32 * TB + tb * 32, acc[fb][tb], r, hh);
;     DI void operator()(int fbase, int tbase, const f32x16& acc, int r, int hh) const {
;         const int t = tbase + r;
;         const bf16_t* res = xb + (size_t)t * D; const float* gate = mods_l + (t >> 13) * 3072 + 2048;
;         float o[16];
; #pragma unroll
;         for (int g = 0; g < 4; ++g) {
;             const int f = fbase + 8 * g + 4 * hh;
;             const u32x2 rb = *(const GAS u32x2*)(res + f); const f32x4 gg = *(const GAS f32x4*)(gate + f);
;             o[4 * g] = bflo(rb.x) + gg.x * acc[4 * g]; o[4 * g + 1] = bfhi(rb.x) + gg.y * acc[4 * g + 1]; o[4 * g + 2] = bflo(rb.y) + gg.z * acc[4 * g + 2]; o[4 * g + 3] = bfhi(rb.y) + gg.w * acc[4 * g + 3];
;         }
;         store_bf16_row32(x2b + (size_t)t * D + fbase, o, hh);
;     }
.LBB0_1173:
	s_ashr_i32 s55, s54, 31
	s_lshr_b32 s55, s55, 30
	s_add_i32 s55, s54, s55
	s_lshr_b32 s56, s55, 2
	s_lshl_b32 s56, s56, s27
	s_and_b32 s55, s55, 0xfffffc
	s_add_i32 s56, s56, s33
	s_sub_i32 s54, s54, s55
	v_lshl_add_u32 v149, s56, 8, v188
	v_lshl_or_b32 v154, s54, 8, v187
	v_or_b32_e32 v166, v149, v183
	v_or_b32_e32 v156, v154, v146
	v_ashrrev_i32_e32 v167, 31, v166
	v_ashrrev_i32_e32 v157, 31, v156
	v_lshlrev_b64 v[160:161], 11, v[166:167]
	v_ashrrev_i32_e32 v149, 13, v149
	v_lshl_add_u64 v[162:163], s[8:9], 0, v[160:161]
	v_lshlrev_b64 v[176:177], 1, v[156:157]
	v_mul_i32_i24_e32 v164, 0xc00, v149
	v_lshl_add_u64 v[158:159], v[162:163], 0, v[176:177]
	v_ashrrev_i32_e32 v165, 31, v164
	global_load_dwordx2 v[200:201], v[158:159], off
	global_load_dwordx2 v[212:213], v[158:159], off offset:16
	global_load_dwordx2 v[214:215], v[158:159], off offset:32
	global_load_dwordx2 v[216:217], v[158:159], off offset:48
	v_or_b32_e32 v170, 8, v156
	v_lshl_add_u64 v[158:159], v[164:165], 2, s[10:11]
	v_ashrrev_i32_e32 v171, 31, v170
	v_or_b32_e32 v172, 16, v156
	v_or_b32_e32 v174, 24, v156
	v_lshl_add_u64 v[158:159], v[158:159], 0, s[40:41]
	v_ashrrev_i32_e32 v173, 31, v172
	v_ashrrev_i32_e32 v175, 31, v174
	v_lshl_add_u64 v[168:169], v[156:157], 2, v[158:159]
	v_lshl_add_u64 v[170:171], v[170:171], 2, v[158:159]
	global_load_dwordx4 v[192:195], v[168:169], off
	global_load_dwordx4 v[196:199], v[170:171], off
	v_lshl_add_u64 v[172:173], v[172:173], 2, v[158:159]
	v_lshl_add_u64 v[174:175], v[174:175], 2, v[158:159]
	global_load_dwordx4 v[204:207], v[172:173], off
	global_load_dwordx4 v[208:211], v[174:175], off
	v_ashrrev_i32_e32 v155, 31, v154
	v_or_b32_e32 v156, 32, v166
	v_lshlrev_b64 v[164:165], 1, v[154:155]
	v_ashrrev_i32_e32 v157, 31, v156
	v_lshl_add_u64 v[160:161], s[12:13], 0, v[160:161]
	v_lshlrev_b64 v[218:219], 11, v[156:157]
	v_lshl_add_u64 v[156:157], v[160:161], 0, v[164:165]
	v_lshl_add_u64 v[160:161], s[8:9], 0, v[218:219]
	v_lshl_add_u64 v[156:157], v[156:157], 0, v[128:129]
	v_lshl_add_u64 v[220:221], v[160:161], 0, v[176:177]
	s_andn2_b64 vcc, exec, s[42:43]
	s_waitcnt vmcnt(0)
	global_load_dwordx2 v[238:239], v[220:221], off
	global_load_dwordx2 v[240:241], v[220:221], off offset:16
	global_load_dwordx2 v[242:243], v[220:221], off offset:32
	global_load_dwordx2 v[244:245], v[220:221], off offset:48
	v_lshlrev_b32_e32 v222, 16, v200
	v_and_b32_e32 v223, 0xffff0000, v200
	v_lshlrev_b32_e32 v200, 16, v201
	v_and_b32_e32 v201, 0xffff0000, v201
	v_lshlrev_b32_e32 v224, 16, v212
	v_and_b32_e32 v225, 0xffff0000, v212
	v_lshlrev_b32_e32 v212, 16, v213
	v_and_b32_e32 v213, 0xffff0000, v213
	v_lshlrev_b32_e32 v226, 16, v214
	v_and_b32_e32 v227, 0xffff0000, v214
	v_lshlrev_b32_e32 v214, 16, v215
	v_and_b32_e32 v215, 0xffff0000, v215
	v_lshlrev_b32_e32 v228, 16, v216
	v_and_b32_e32 v229, 0xffff0000, v216
	v_lshlrev_b32_e32 v216, 16, v217
	v_and_b32_e32 v217, 0xffff0000, v217
	v_pk_fma_f32 v[112:113], v[112:113], v[192:193], v[222:223]
	v_pk_fma_f32 v[114:115], v[114:115], v[194:195], v[200:201]
	v_pk_fma_f32 v[116:117], v[116:117], v[196:197], v[224:225]
	v_pk_fma_f32 v[118:119], v[118:119], v[198:199], v[212:213]
	v_pk_fma_f32 v[120:121], v[120:121], v[204:205], v[226:227]
	v_pk_fma_f32 v[122:123], v[122:123], v[206:207], v[214:215]
	v_pk_fma_f32 v[124:125], v[124:125], v[208:209], v[228:229]
	v_pk_fma_f32 v[126:127], v[126:127], v[210:211], v[216:217]
	v_cvt_pk_bf16_f32 v112, v112, v113
	v_cvt_pk_bf16_f32 v113, v114, v115
	v_cvt_pk_bf16_f32 v114, v116, v117
	v_cvt_pk_bf16_f32 v115, v118, v119
	v_cvt_pk_bf16_f32 v116, v120, v121
	v_cvt_pk_bf16_f32 v117, v122, v123
	v_cvt_pk_bf16_f32 v118, v124, v125
	v_cvt_pk_bf16_f32 v119, v126, v127
	v_permlane32_swap_b32_e32 v112, v114
	v_permlane32_swap_b32_e32 v113, v115
	v_permlane32_swap_b32_e32 v116, v118
	v_permlane32_swap_b32_e32 v117, v119
	global_store_dwordx4 v[156:157], v[112:115], off
	global_store_dwordx4 v[156:157], v[116:119], off offset:32
	s_nop 0
	global_load_dwordx4 v[116:119], v[168:169], off
	global_load_dwordx4 v[120:123], v[170:171], off
	global_load_dwordx4 v[124:127], v[172:173], off
	global_load_dwordx4 v[192:195], v[174:175], off
	v_or_b32_e32 v112, 64, v166
	v_ashrrev_i32_e32 v113, 31, v112
	v_lshlrev_b64 v[206:207], 11, v[112:113]
	v_lshl_add_u64 v[112:113], s[12:13], 0, v[218:219]
	v_lshl_add_u64 v[112:113], v[112:113], 0, v[164:165]
	v_lshl_add_u64 v[114:115], s[8:9], 0, v[206:207]
	v_lshl_add_u64 v[112:113], v[112:113], 0, v[128:129]
	v_lshl_add_u64 v[208:209], v[114:115], 0, v[176:177]
	s_waitcnt vmcnt(0)
; #define GAS __attribute__((address_space(1)))
; DI float bflo(unsigned u) { return __uint_as_float(u << 16); }
; DI float bfhi(unsigned u) { return __uint_as_float(u & 0xffff0000u); }
;     DI void operator()(int fbase, int tbase, const f32x16& acc, int r, int hh) const {
;         const int t = tbase + r;
;         const bf16_t* res = xb + (size_t)t * D; const float* gate = mods_l + (t >> 13) * 3072 + 2048;
;         float o[16];
; #pragma unroll
;         for (int g = 0; g < 4; ++g) {
;             const int f = fbase + 8 * g + 4 * hh;
;             const u32x2 rb = *(const GAS u32x2*)(res + f); const f32x4 gg = *(const GAS f32x4*)(gate + f);
;             o[4 * g] = bflo(rb.x) + gg.x * acc[4 * g]; o[4 * g + 1] = bfhi(rb.x) + gg.y * acc[4 * g + 1]; o[4 * g + 2] = bflo(rb.y) + gg.z * acc[4 * g + 2]; o[4 * g + 3] = bfhi(rb.y) + gg.w * acc[4 * g + 3];
;         }
;         store_bf16_row32(x2b + (size_t)t * D + fbase, o, hh);
;     }
	global_load_dwordx2 v[230:231], v[208:209], off
	global_load_dwordx2 v[232:233], v[208:209], off offset:16
	global_load_dwordx2 v[234:235], v[208:209], off offset:32
	global_load_dwordx2 v[236:237], v[208:209], off offset:48
	v_lshlrev_b32_e32 v210, 16, v238
	v_and_b32_e32 v211, 0xffff0000, v238
	v_lshlrev_b32_e32 v196, 16, v239
	v_and_b32_e32 v197, 0xffff0000, v239
	v_lshlrev_b32_e32 v212, 16, v240
	v_and_b32_e32 v213, 0xffff0000, v240
	v_lshlrev_b32_e32 v198, 16, v241
	v_and_b32_e32 v199, 0xffff0000, v241
	v_lshlrev_b32_e32 v214, 16, v242
	v_and_b32_e32 v215, 0xffff0000, v242
	v_lshlrev_b32_e32 v200, 16, v243
	v_and_b32_e32 v201, 0xffff0000, v243
	v_lshlrev_b32_e32 v216, 16, v244
	v_and_b32_e32 v217, 0xffff0000, v244
	v_lshlrev_b32_e32 v204, 16, v245
	v_and_b32_e32 v205, 0xffff0000, v245
	v_pk_fma_f32 v[96:97], v[96:97], v[116:117], v[210:211]
	v_pk_fma_f32 v[98:99], v[98:99], v[118:119], v[196:197]
	v_pk_fma_f32 v[100:101], v[100:101], v[120:121], v[212:213]
	v_pk_fma_f32 v[102:103], v[102:103], v[122:123], v[198:199]
	v_pk_fma_f32 v[104:105], v[104:105], v[124:125], v[214:215]
	v_pk_fma_f32 v[106:107], v[106:107], v[126:127], v[200:201]
	v_pk_fma_f32 v[108:109], v[108:109], v[192:193], v[216:217]
	v_pk_fma_f32 v[110:111], v[110:111], v[194:195], v[204:205]
	v_cvt_pk_bf16_f32 v96, v96, v97
	v_cvt_pk_bf16_f32 v97, v98, v99
	v_cvt_pk_bf16_f32 v98, v100, v101
	v_cvt_pk_bf16_f32 v99, v102, v103
	v_cvt_pk_bf16_f32 v100, v104, v105
	v_cvt_pk_bf16_f32 v101, v106, v107
	v_cvt_pk_bf16_f32 v102, v108, v109
	v_cvt_pk_bf16_f32 v103, v110, v111
	v_permlane32_swap_b32_e32 v96, v98
	v_permlane32_swap_b32_e32 v97, v99
	v_permlane32_swap_b32_e32 v100, v102
	v_permlane32_swap_b32_e32 v101, v103
	global_store_dwordx4 v[112:113], v[96:99], off
	global_store_dwordx4 v[112:113], v[100:103], off offset:32
	s_nop 0
	global_load_dwordx4 v[100:103], v[168:169], off
	global_load_dwordx4 v[104:107], v[170:171], off
	global_load_dwordx4 v[108:111], v[172:173], off
	global_load_dwordx4 v[116:119], v[174:175], off
	v_or_b32_e32 v96, 0x60, v166
	v_ashrrev_i32_e32 v97, 31, v96
	v_lshlrev_b64 v[166:167], 11, v[96:97]
	v_lshl_add_u64 v[96:97], s[12:13], 0, v[206:207]
	v_lshl_add_u64 v[96:97], v[96:97], 0, v[164:165]
	v_lshl_add_u64 v[98:99], s[8:9], 0, v[166:167]
	v_lshl_add_u64 v[96:97], v[96:97], 0, v[128:129]
	v_lshl_add_u64 v[176:177], v[98:99], 0, v[176:177]
	s_waitcnt vmcnt(0)
	global_load_dwordx2 v[238:239], v[176:177], off
	global_load_dwordx2 v[240:241], v[176:177], off offset:16
	global_load_dwordx2 v[242:243], v[176:177], off offset:32
	global_load_dwordx2 v[244:245], v[176:177], off offset:48
	v_lshlrev_b32_e32 v192, 16, v230
	v_and_b32_e32 v193, 0xffff0000, v230
	v_lshlrev_b32_e32 v120, 16, v231
	v_and_b32_e32 v121, 0xffff0000, v231
	v_lshlrev_b32_e32 v194, 16, v232
	v_and_b32_e32 v195, 0xffff0000, v232
	v_lshlrev_b32_e32 v122, 16, v233
	v_and_b32_e32 v123, 0xffff0000, v233
	v_lshlrev_b32_e32 v196, 16, v234
	v_and_b32_e32 v197, 0xffff0000, v234
	v_lshlrev_b32_e32 v124, 16, v235
	v_and_b32_e32 v125, 0xffff0000, v235
	v_lshlrev_b32_e32 v198, 16, v236
	v_and_b32_e32 v199, 0xffff0000, v236
	v_lshlrev_b32_e32 v126, 16, v237
	v_and_b32_e32 v127, 0xffff0000, v237
	v_pk_fma_f32 v[80:81], v[80:81], v[100:101], v[192:193]
	v_pk_fma_f32 v[82:83], v[82:83], v[102:103], v[120:121]
	v_pk_fma_f32 v[84:85], v[84:85], v[104:105], v[194:195]
	v_pk_fma_f32 v[86:87], v[86:87], v[106:107], v[122:123]
	v_pk_fma_f32 v[88:89], v[88:89], v[108:109], v[196:197]
	v_pk_fma_f32 v[90:91], v[90:91], v[110:111], v[124:125]
	v_pk_fma_f32 v[92:93], v[92:93], v[116:117], v[198:199]
	v_pk_fma_f32 v[94:95], v[94:95], v[118:119], v[126:127]
	v_cvt_pk_bf16_f32 v80, v80, v81
	v_cvt_pk_bf16_f32 v81, v82, v83
	v_cvt_pk_bf16_f32 v82, v84, v85
	v_cvt_pk_bf16_f32 v83, v86, v87
	v_cvt_pk_bf16_f32 v84, v88, v89
	v_cvt_pk_bf16_f32 v85, v90, v91
	v_cvt_pk_bf16_f32 v86, v92, v93
	v_cvt_pk_bf16_f32 v87, v94, v95
	v_permlane32_swap_b32_e32 v80, v82
	v_permlane32_swap_b32_e32 v81, v83
	v_permlane32_swap_b32_e32 v84, v86
	v_permlane32_swap_b32_e32 v85, v87
	global_store_dwordx4 v[96:97], v[80:83], off
	global_store_dwordx4 v[96:97], v[84:87], off offset:32
	s_nop 0
	global_load_dwordx4 v[84:87], v[168:169], off
	global_load_dwordx4 v[88:91], v[170:171], off
	global_load_dwordx4 v[92:95], v[172:173], off
	global_load_dwordx4 v[100:103], v[174:175], off
	v_lshl_add_u64 v[80:81], v[154:155], 0, v[146:147]
	v_lshlrev_b64 v[82:83], 1, v[80:81]
	v_lshl_add_u64 v[80:81], s[12:13], 0, v[166:167]
	v_lshl_add_u64 v[80:81], v[80:81], 0, v[164:165]
	v_lshl_add_u64 v[80:81], v[80:81], 0, v[128:129]
	v_lshl_add_u64 v[116:117], v[162:163], 0, v[82:83]
	s_waitcnt vmcnt(0)
; #define GAS __attribute__((address_space(1)))
; DI float bflo(unsigned u) { return __uint_as_float(u << 16); }
; DI float bfhi(unsigned u) { return __uint_as_float(u & 0xffff0000u); }
;     DI void operator()(int fbase, int tbase, const f32x16& acc, int r, int hh) const {
;         const int t = tbase + r;
;         const bf16_t* res = xb + (size_t)t * D; const float* gate = mods_l + (t >> 13) * 3072 + 2048;
;         float o[16];
; #pragma unroll
;         for (int g = 0; g < 4; ++g) {
;             const int f = fbase + 8 * g + 4 * hh;
;             const u32x2 rb = *(const GAS u32x2*)(res + f); const f32x4 gg = *(const GAS f32x4*)(gate + f);
;             o[4 * g] = bflo(rb.x) + gg.x * acc[4 * g]; o[4 * g + 1] = bfhi(rb.x) + gg.y * acc[4 * g + 1]; o[4 * g + 2] = bflo(rb.y) + gg.z * acc[4 * g + 2]; o[4 * g + 3] = bfhi(rb.y) + gg.w * acc[4 * g + 3];
;         }
;         store_bf16_row32(x2b + (size_t)t * D + fbase, o, hh);
;     }
	global_load_dwordx2 v[230:231], v[116:117], off offset:64
	global_load_dwordx2 v[232:233], v[116:117], off offset:80
	global_load_dwordx2 v[234:235], v[116:117], off offset:96
	global_load_dwordx2 v[236:237], v[116:117], off offset:112
	v_lshlrev_b32_e32 v118, 16, v238
	v_and_b32_e32 v119, 0xffff0000, v238
	v_lshlrev_b32_e32 v104, 16, v239
	v_and_b32_e32 v105, 0xffff0000, v239
	v_lshlrev_b32_e32 v120, 16, v240
	v_and_b32_e32 v121, 0xffff0000, v240
	v_lshlrev_b32_e32 v106, 16, v241
	v_and_b32_e32 v107, 0xffff0000, v241
	v_lshlrev_b32_e32 v122, 16, v242
	v_and_b32_e32 v123, 0xffff0000, v242
	v_lshlrev_b32_e32 v108, 16, v243
	v_and_b32_e32 v109, 0xffff0000, v243
	v_lshlrev_b32_e32 v124, 16, v244
	v_and_b32_e32 v125, 0xffff0000, v244
	v_lshlrev_b32_e32 v110, 16, v245
	v_and_b32_e32 v111, 0xffff0000, v245
	v_pk_fma_f32 v[64:65], v[64:65], v[84:85], v[118:119]
	v_pk_fma_f32 v[66:67], v[66:67], v[86:87], v[104:105]
	v_pk_fma_f32 v[68:69], v[68:69], v[88:89], v[120:121]
	v_pk_fma_f32 v[70:71], v[70:71], v[90:91], v[106:107]
	v_pk_fma_f32 v[72:73], v[72:73], v[92:93], v[122:123]
	v_pk_fma_f32 v[74:75], v[74:75], v[94:95], v[108:109]
	v_pk_fma_f32 v[76:77], v[76:77], v[100:101], v[124:125]
	v_pk_fma_f32 v[78:79], v[78:79], v[102:103], v[110:111]
	v_cvt_pk_bf16_f32 v64, v64, v65
	v_cvt_pk_bf16_f32 v65, v66, v67
	v_cvt_pk_bf16_f32 v66, v68, v69
	v_cvt_pk_bf16_f32 v67, v70, v71
	v_cvt_pk_bf16_f32 v68, v72, v73
	v_cvt_pk_bf16_f32 v69, v74, v75
	v_cvt_pk_bf16_f32 v70, v76, v77
	v_cvt_pk_bf16_f32 v71, v78, v79
	v_permlane32_swap_b32_e32 v64, v66
	v_permlane32_swap_b32_e32 v65, v67
	v_permlane32_swap_b32_e32 v68, v70
	v_permlane32_swap_b32_e32 v69, v71
	global_store_dwordx4 v[80:81], v[64:67], off
	global_store_dwordx4 v[80:81], v[68:71], off offset:32
	v_or_b32_e32 v64, v154, v191
	v_or_b32_e32 v66, 8, v64
	v_ashrrev_i32_e32 v65, 31, v64
	v_or_b32_e32 v68, 16, v64
	v_or_b32_e32 v70, 24, v64
	v_ashrrev_i32_e32 v67, 31, v66
	v_ashrrev_i32_e32 v69, 31, v68
	v_ashrrev_i32_e32 v71, 31, v70
	v_lshl_add_u64 v[64:65], v[64:65], 2, v[158:159]
	v_lshl_add_u64 v[66:67], v[66:67], 2, v[158:159]
	global_load_dwordx4 v[72:75], v[64:65], off
	global_load_dwordx4 v[76:79], v[66:67], off
	v_lshl_add_u64 v[68:69], v[68:69], 2, v[158:159]
	v_lshl_add_u64 v[70:71], v[70:71], 2, v[158:159]
	global_load_dwordx4 v[84:87], v[68:69], off
	global_load_dwordx4 v[88:91], v[70:71], off
	v_lshl_add_u64 v[104:105], v[160:161], 0, v[82:83]
	s_waitcnt vmcnt(0)
	global_load_dwordx2 v[238:239], v[104:105], off offset:64
	global_load_dwordx2 v[240:241], v[104:105], off offset:80
	global_load_dwordx2 v[242:243], v[104:105], off offset:96
	global_load_dwordx2 v[244:245], v[104:105], off offset:112
	v_lshlrev_b32_e32 v106, 16, v230
	v_and_b32_e32 v107, 0xffff0000, v230
	v_lshlrev_b32_e32 v92, 16, v231
	v_and_b32_e32 v93, 0xffff0000, v231
	v_lshlrev_b32_e32 v108, 16, v232
	v_and_b32_e32 v109, 0xffff0000, v232
	v_lshlrev_b32_e32 v94, 16, v233
	v_and_b32_e32 v95, 0xffff0000, v233
	v_lshlrev_b32_e32 v110, 16, v234
	v_and_b32_e32 v111, 0xffff0000, v234
	v_lshlrev_b32_e32 v100, 16, v235
	v_and_b32_e32 v101, 0xffff0000, v235
	v_lshlrev_b32_e32 v116, 16, v236
	v_and_b32_e32 v117, 0xffff0000, v236
	v_lshlrev_b32_e32 v102, 16, v237
	v_and_b32_e32 v103, 0xffff0000, v237
	v_pk_fma_f32 v[48:49], v[48:49], v[72:73], v[106:107]
	v_pk_fma_f32 v[50:51], v[50:51], v[74:75], v[92:93]
	v_pk_fma_f32 v[52:53], v[52:53], v[76:77], v[108:109]
	v_pk_fma_f32 v[54:55], v[54:55], v[78:79], v[94:95]
	v_pk_fma_f32 v[56:57], v[56:57], v[84:85], v[110:111]
	v_pk_fma_f32 v[58:59], v[58:59], v[86:87], v[100:101]
	v_pk_fma_f32 v[60:61], v[60:61], v[88:89], v[116:117]
	v_pk_fma_f32 v[62:63], v[62:63], v[90:91], v[102:103]
	v_cvt_pk_bf16_f32 v48, v48, v49
	v_cvt_pk_bf16_f32 v49, v50, v51
	v_cvt_pk_bf16_f32 v50, v52, v53
	v_cvt_pk_bf16_f32 v51, v54, v55
	v_cvt_pk_bf16_f32 v52, v56, v57
	v_cvt_pk_bf16_f32 v53, v58, v59
	v_cvt_pk_bf16_f32 v54, v60, v61
	v_cvt_pk_bf16_f32 v55, v62, v63
	v_permlane32_swap_b32_e32 v48, v50
	v_permlane32_swap_b32_e32 v49, v51
	v_permlane32_swap_b32_e32 v52, v54
	v_permlane32_swap_b32_e32 v53, v55
	global_store_dwordx4 v[156:157], v[48:51], off offset:64
	global_store_dwordx4 v[156:157], v[52:55], off offset:96
	global_load_dwordx4 v[48:51], v[64:65], off
	global_load_dwordx4 v[52:55], v[66:67], off
	global_load_dwordx4 v[56:59], v[68:69], off
	global_load_dwordx4 v[60:63], v[70:71], off
	v_lshl_add_u64 v[84:85], v[114:115], 0, v[82:83]
	s_waitcnt vmcnt(0)
; #define GAS __attribute__((address_space(1)))
; DI float bflo(unsigned u) { return __uint_as_float(u << 16); }
; DI float bfhi(unsigned u) { return __uint_as_float(u & 0xffff0000u); }
;     DI void operator()(int fbase, int tbase, const f32x16& acc, int r, int hh) const {
;         const int t = tbase + r;
;         const bf16_t* res = xb + (size_t)t * D; const float* gate = mods_l + (t >> 13) * 3072 + 2048;
;         float o[16];
; #pragma unroll
;         for (int g = 0; g < 4; ++g) {
;             const int f = fbase + 8 * g + 4 * hh;
;             const u32x2 rb = *(const GAS u32x2*)(res + f); const f32x4 gg = *(const GAS f32x4*)(gate + f);
;             o[4 * g] = bflo(rb.x) + gg.x * acc[4 * g]; o[4 * g + 1] = bfhi(rb.x) + gg.y * acc[4 * g + 1]; o[4 * g + 2] = bflo(rb.y) + gg.z * acc[4 * g + 2]; o[4 * g + 3] = bfhi(rb.y) + gg.w * acc[4 * g + 3];
;         }
;         store_bf16_row32(x2b + (size_t)t * D + fbase, o, hh);
;     }
	global_load_dwordx2 v[230:231], v[84:85], off offset:64
	global_load_dwordx2 v[232:233], v[84:85], off offset:80
	global_load_dwordx2 v[234:235], v[84:85], off offset:96
	global_load_dwordx2 v[236:237], v[84:85], off offset:112
	v_lshlrev_b32_e32 v86, 16, v238
	v_and_b32_e32 v87, 0xffff0000, v238
	v_lshlrev_b32_e32 v72, 16, v239
	v_and_b32_e32 v73, 0xffff0000, v239
	v_lshlrev_b32_e32 v88, 16, v240
	v_and_b32_e32 v89, 0xffff0000, v240
	v_lshlrev_b32_e32 v74, 16, v241
	v_and_b32_e32 v75, 0xffff0000, v241
	v_lshlrev_b32_e32 v90, 16, v242
	v_and_b32_e32 v91, 0xffff0000, v242
	v_lshlrev_b32_e32 v76, 16, v243
	v_and_b32_e32 v77, 0xffff0000, v243
	v_lshlrev_b32_e32 v92, 16, v244
	v_and_b32_e32 v93, 0xffff0000, v244
	v_lshlrev_b32_e32 v78, 16, v245
	v_and_b32_e32 v79, 0xffff0000, v245
	v_pk_fma_f32 v[32:33], v[32:33], v[48:49], v[86:87]
	v_pk_fma_f32 v[34:35], v[34:35], v[50:51], v[72:73]
	v_pk_fma_f32 v[36:37], v[36:37], v[52:53], v[88:89]
	v_pk_fma_f32 v[38:39], v[38:39], v[54:55], v[74:75]
	v_pk_fma_f32 v[40:41], v[40:41], v[56:57], v[90:91]
	v_pk_fma_f32 v[42:43], v[42:43], v[58:59], v[76:77]
	v_pk_fma_f32 v[44:45], v[44:45], v[60:61], v[92:93]
	v_pk_fma_f32 v[46:47], v[46:47], v[62:63], v[78:79]
	v_cvt_pk_bf16_f32 v32, v32, v33
	v_cvt_pk_bf16_f32 v33, v34, v35
	v_cvt_pk_bf16_f32 v34, v36, v37
	v_cvt_pk_bf16_f32 v35, v38, v39
	v_cvt_pk_bf16_f32 v36, v40, v41
	v_cvt_pk_bf16_f32 v37, v42, v43
	v_cvt_pk_bf16_f32 v38, v44, v45
	v_cvt_pk_bf16_f32 v39, v46, v47
	v_permlane32_swap_b32_e32 v32, v34
	v_permlane32_swap_b32_e32 v33, v35
	v_permlane32_swap_b32_e32 v36, v38
	v_permlane32_swap_b32_e32 v37, v39
	global_store_dwordx4 v[112:113], v[32:35], off offset:64
	global_store_dwordx4 v[112:113], v[36:39], off offset:96
	global_load_dwordx4 v[32:35], v[64:65], off
	global_load_dwordx4 v[36:39], v[66:67], off
	global_load_dwordx4 v[40:43], v[68:69], off
	global_load_dwordx4 v[44:47], v[70:71], off
	v_lshl_add_u64 v[56:57], v[98:99], 0, v[82:83]
	s_waitcnt vmcnt(0)
	global_load_dwordx2 v[238:239], v[56:57], off offset:64
	global_load_dwordx2 v[240:241], v[56:57], off offset:80
	global_load_dwordx2 v[242:243], v[56:57], off offset:96
	global_load_dwordx2 v[244:245], v[56:57], off offset:112
	v_lshlrev_b32_e32 v58, 16, v230
	v_and_b32_e32 v59, 0xffff0000, v230
	v_lshlrev_b32_e32 v48, 16, v231
	v_and_b32_e32 v49, 0xffff0000, v231
	v_lshlrev_b32_e32 v60, 16, v232
	v_and_b32_e32 v61, 0xffff0000, v232
	v_lshlrev_b32_e32 v50, 16, v233
	v_and_b32_e32 v51, 0xffff0000, v233
	v_lshlrev_b32_e32 v62, 16, v234
	v_and_b32_e32 v63, 0xffff0000, v234
	v_lshlrev_b32_e32 v52, 16, v235
	v_and_b32_e32 v53, 0xffff0000, v235
	v_lshlrev_b32_e32 v72, 16, v236
	v_and_b32_e32 v73, 0xffff0000, v236
	v_lshlrev_b32_e32 v54, 16, v237
	v_and_b32_e32 v55, 0xffff0000, v237
	v_pk_fma_f32 v[16:17], v[16:17], v[32:33], v[58:59]
	v_pk_fma_f32 v[18:19], v[18:19], v[34:35], v[48:49]
	v_pk_fma_f32 v[20:21], v[20:21], v[36:37], v[60:61]
	v_pk_fma_f32 v[22:23], v[22:23], v[38:39], v[50:51]
	v_pk_fma_f32 v[24:25], v[24:25], v[40:41], v[62:63]
	v_pk_fma_f32 v[26:27], v[26:27], v[42:43], v[52:53]
	v_pk_fma_f32 v[28:29], v[28:29], v[44:45], v[72:73]
	v_pk_fma_f32 v[30:31], v[30:31], v[46:47], v[54:55]
	v_cvt_pk_bf16_f32 v16, v16, v17
	v_cvt_pk_bf16_f32 v17, v18, v19
	v_cvt_pk_bf16_f32 v18, v20, v21
	v_cvt_pk_bf16_f32 v19, v22, v23
	v_cvt_pk_bf16_f32 v20, v24, v25
	v_cvt_pk_bf16_f32 v21, v26, v27
	v_cvt_pk_bf16_f32 v22, v28, v29
	v_cvt_pk_bf16_f32 v23, v30, v31
	v_permlane32_swap_b32_e32 v16, v18
	v_permlane32_swap_b32_e32 v17, v19
	v_permlane32_swap_b32_e32 v20, v22
	v_permlane32_swap_b32_e32 v21, v23
	global_store_dwordx4 v[96:97], v[16:19], off offset:64
	global_store_dwordx4 v[96:97], v[20:23], off offset:96
	global_load_dwordx4 v[16:19], v[64:65], off
	global_load_dwordx4 v[20:23], v[66:67], off
	global_load_dwordx4 v[24:27], v[68:69], off
	global_load_dwordx4 v[28:31], v[70:71], off
	s_waitcnt vmcnt(0)
	v_lshlrev_b32_e32 v40, 16, v238
	v_and_b32_e32 v41, 0xffff0000, v238
	v_lshlrev_b32_e32 v32, 16, v239
	v_and_b32_e32 v33, 0xffff0000, v239
	v_lshlrev_b32_e32 v42, 16, v240
	v_and_b32_e32 v43, 0xffff0000, v240
	v_lshlrev_b32_e32 v34, 16, v241
	v_and_b32_e32 v35, 0xffff0000, v241
	v_lshlrev_b32_e32 v44, 16, v242
	v_and_b32_e32 v45, 0xffff0000, v242
	v_lshlrev_b32_e32 v36, 16, v243
	v_and_b32_e32 v37, 0xffff0000, v243
	v_lshlrev_b32_e32 v46, 16, v244
	v_and_b32_e32 v47, 0xffff0000, v244
	v_lshlrev_b32_e32 v38, 16, v245
	v_and_b32_e32 v39, 0xffff0000, v245
	v_pk_fma_f32 v[0:1], v[0:1], v[16:17], v[40:41]
	v_pk_fma_f32 v[2:3], v[2:3], v[18:19], v[32:33]
	v_pk_fma_f32 v[4:5], v[4:5], v[20:21], v[42:43]
	v_pk_fma_f32 v[6:7], v[6:7], v[22:23], v[34:35]
	v_pk_fma_f32 v[8:9], v[8:9], v[24:25], v[44:45]
	v_pk_fma_f32 v[10:11], v[10:11], v[26:27], v[36:37]
	v_pk_fma_f32 v[12:13], v[12:13], v[28:29], v[46:47]
	v_pk_fma_f32 v[14:15], v[14:15], v[30:31], v[38:39]
	v_cvt_pk_bf16_f32 v0, v0, v1
	v_cvt_pk_bf16_f32 v1, v2, v3
	v_cvt_pk_bf16_f32 v2, v4, v5
	v_cvt_pk_bf16_f32 v3, v6, v7
	v_cvt_pk_bf16_f32 v4, v8, v9
	v_cvt_pk_bf16_f32 v5, v10, v11
	v_cvt_pk_bf16_f32 v6, v12, v13
	v_cvt_pk_bf16_f32 v7, v14, v15
	v_permlane32_swap_b32_e32 v0, v2
	v_permlane32_swap_b32_e32 v1, v3
	v_permlane32_swap_b32_e32 v4, v6
	v_permlane32_swap_b32_e32 v5, v7
	global_store_dwordx4 v[80:81], v[0:3], off offset:64
	global_store_dwordx4 v[80:81], v[4:7], off offset:96
	s_cbranch_vccz .LBB0_1168
